# weight-conversion items >= 2048 moved into the idle tail of P2 (workgroups >= 128 have one GEMM tile fewer)
# speedup vs baseline: 1.0196x; 1.0048x over previous
.Lp01_bb36:
	v_lshrrev_b32_e32 v17, 5, v140
	s_movk_i32 s1, 0x84
	v_mov_b32_e32 v0, 0x108
	v_mad_u32_u24 v21, v17, s1, v0
	v_mov_b32_e32 v0, 0x210
	v_mad_u32_u24 v23, v17, s1, v0
	v_mov_b32_e32 v0, 0x318
	v_mad_u32_u24 v25, v17, s1, v0
	v_mov_b32_e32 v0, 0x420
	v_mad_u32_u24 v27, v17, s1, v0
	v_mov_b32_e32 v0, 0x528
	v_mad_u32_u24 v29, v17, s1, v0
	v_mov_b32_e32 v0, 0x630
	v_mad_u32_u24 v31, v17, s1, v0
	v_mov_b32_e32 v0, 0x738
	v_mad_u32_u24 v33, v17, s1, v0
	v_mov_b32_e32 v0, 0x840
	v_mad_u32_u24 v35, v17, s1, v0
	v_mov_b32_e32 v0, 0x948
	v_mad_u32_u24 v37, v17, s1, v0
	v_mov_b32_e32 v0, 0xa50
	v_mad_u32_u24 v39, v17, s1, v0
	v_mov_b32_e32 v0, 0xb58
	v_mad_u32_u24 v41, v17, s1, v0
	v_mov_b32_e32 v0, 0xc60
	v_mad_u32_u24 v43, v17, s1, v0
	v_mov_b32_e32 v0, 0xd68
	v_mad_u32_u24 v45, v17, s1, v0
	v_mov_b32_e32 v0, 0xe70
	v_mad_u32_u24 v47, v17, s1, v0
	v_mov_b32_e32 v0, 0xf78
	v_mad_u32_u24 v49, v17, s1, v0
	v_mov_b32_e32 v0, 0x1080
	v_mad_u32_u24 v51, v17, s1, v0
	v_mov_b32_e32 v0, 0x1188
	v_mad_u32_u24 v53, v17, s1, v0
	v_mov_b32_e32 v0, 0x1290
	v_mad_u32_u24 v55, v17, s1, v0
	v_mov_b32_e32 v0, 0x1398
	v_mad_u32_u24 v57, v17, s1, v0
	v_mov_b32_e32 v0, 0x14a0
	v_mad_u32_u24 v59, v17, s1, v0
	v_mov_b32_e32 v0, 0x15a8
	v_mad_u32_u24 v61, v17, s1, v0
	v_mov_b32_e32 v0, 0x16b0
	v_mad_u32_u24 v63, v17, s1, v0
	v_mov_b32_e32 v0, 0x17b8
	v_mad_u32_u24 v65, v17, s1, v0
	v_mov_b32_e32 v0, 0x18c0
	v_mad_u32_u24 v67, v17, s1, v0
	v_lshlrev_b32_e32 v0, 3, v140
	s_lshl_b32 s0, s60, 14
	v_lshrrev_b32_e32 v75, 3, v140
	v_and_b32_e32 v0, 56, v0
	s_add_i32 s0, s0, 0
	v_and_b32_e32 v16, 31, v141
	v_mul_u32_u24_e32 v4, 0x84, v0
	v_lshlrev_b32_e32 v5, 2, v75
	v_readlane_b32 s16, v254, 31
	v_lshl_add_u32 v18, v16, 2, s0
	v_add3_u32 v76, s0, v4, v5
	v_readlane_b32 s0, v254, 29
	v_readlane_b32 s17, v254, 32
	v_readlane_b32 s18, v254, 33
	v_readlane_b32 s19, v254, 34
	v_readlane_b32 s20, v254, 35
	v_readlane_b32 s21, v254, 36
	v_readlane_b32 s22, v254, 37
	v_readlane_b32 s23, v254, 38
	v_readlane_b32 s24, v254, 39
	v_readlane_b32 s25, v254, 40
	v_readlane_b32 s26, v254, 41
	v_readlane_b32 s27, v254, 42
	v_readlane_b32 s28, v254, 43
	v_readlane_b32 s29, v254, 44
	v_readlane_b32 s30, v254, 45
	v_readlane_b32 s31, v254, 46
	v_lshlrev_b32_e32 v0, 1, v0
	v_mov_b32_e32 v1, 0
	v_readlane_b32 s1, v254, 30
	s_cmp_lg_u64 s[18:19], 0
	v_readlane_b32 s16, v254, 3
	v_lshl_add_u64 v[4:5], s[0:1], 0, v[0:1]
	v_readlane_b32 s0, v254, 27
	v_readlane_b32 s30, v254, 17
	v_readlane_b32 s31, v254, 18
	v_readlane_b32 s1, v254, 28
	s_cselect_b64 s[6:7], -1, 0
	s_cmp_lg_u64 s[30:31], 0
	v_lshl_add_u64 v[6:7], s[0:1], 0, v[0:1]
	v_readlane_b32 s0, v254, 21
	s_cselect_b64 s[8:9], -1, 0
	s_cmp_eq_u32 s98, 4
	s_cbranch_scc0 .Lit_noadj
	s_add_i32 s0, s0, 0x400
.Lit_noadj:
	s_mov_b32 s4, s0
	s_lshl_b32 s0, s0, 5
	v_readlane_b32 s17, v254, 4
	v_readlane_b32 s18, v254, 5
	v_readlane_b32 s19, v254, 6
	v_readlane_b32 s20, v254, 7
	v_readlane_b32 s21, v254, 8
	v_readlane_b32 s22, v254, 9
	v_readlane_b32 s23, v254, 10
	v_readlane_b32 s24, v254, 11
	v_readlane_b32 s25, v254, 12
	v_readlane_b32 s26, v254, 13
	v_readlane_b32 s27, v254, 14
	v_readlane_b32 s28, v254, 15
	v_readlane_b32 s29, v254, 16
	s_add_i32 s16, s0, 0xfffdae00
	s_lshl_b32 s0, s4, 1
	s_mov_b32 s5, 0
	v_mul_u32_u24_e32 v19, 0x84, v17
	v_or_b32_e32 v20, 2, v17
	v_or_b32_e32 v22, 4, v17
	v_or_b32_e32 v24, 6, v17
	v_or_b32_e32 v26, 8, v17
	v_or_b32_e32 v28, 10, v17
	v_or_b32_e32 v30, 12, v17
	v_or_b32_e32 v32, 14, v17
	v_or_b32_e32 v34, 16, v17
	v_or_b32_e32 v36, 18, v17
	v_or_b32_e32 v38, 20, v17
	v_or_b32_e32 v40, 22, v17
	v_or_b32_e32 v42, 24, v17
	v_or_b32_e32 v44, 26, v17
	v_or_b32_e32 v46, 28, v17
	v_or_b32_e32 v48, 30, v17
	v_or_b32_e32 v50, 32, v17
	v_or_b32_e32 v52, 34, v17
	v_or_b32_e32 v54, 36, v17
	v_or_b32_e32 v56, 38, v17
	v_or_b32_e32 v58, 40, v17
	v_or_b32_e32 v60, 42, v17
	v_or_b32_e32 v62, 44, v17
	v_or_b32_e32 v64, 46, v17
	v_or_b32_e32 v66, 48, v17
	v_or_b32_e32 v68, 50, v17
	v_or_b32_e32 v69, 52, v17
	v_or_b32_e32 v70, 54, v17
	v_or_b32_e32 v71, 56, v17
	v_or_b32_e32 v72, 58, v17
	v_or_b32_e32 v73, 60, v17
	v_or_b32_e32 v74, 62, v17
	v_lshl_add_u64 v[2:3], s[84:85], 0, v[0:1]
	v_or_b32_e32 v77, 8, v75
	v_or_b32_e32 v78, 16, v75
	v_or_b32_e32 v79, 24, v75
	v_bfe_u32 v80, v140, 3, 2
	v_lshl_add_u64 v[8:9], s[12:13], 0, v[0:1]
	v_lshl_add_u64 v[10:11], s[14:15], 0, v[0:1]
	v_lshl_add_u64 v[12:13], s[2:3], 0, v[0:1]
	s_lshl_b32 s17, s52, 5
	s_add_i32 s18, s0, 0xffffdae0
	s_lshl_b32 s19, s52, 1
	s_movk_i32 s20, 0x1fc8
	s_movk_i32 s21, 0x1fd8
	s_movk_i32 s22, 0x1fe8
	s_movk_i32 s23, 0x1ff8
	s_movk_i32 s24, 0xc00
	s_movk_i32 s25, 0x50
	s_movk_i32 s26, 0x300
	s_movk_i32 s27, 0x8a7
	s_movk_i32 s28, 0x22a0
	v_mov_b32_e32 v81, 0x2000
	v_mov_b32_e32 v82, 0xffffff61
	v_mov_b32_e32 v83, 0xffffff80
	s_mov_b32 s29, s4
	v_readlane_b32 s1, v254, 22
	s_branch .LBB0_39

.LBB0_38:
	s_cmp_lg_u32 s98, 4
	s_cbranch_scc1 .LBB0_226
	s_add_i32 s29, s29, s52
	s_add_i32 s16, s16, s17
	s_add_i32 s18, s18, s19
	s_cmpk_gt_i32 s29, 0x180f
	s_cbranch_scc1 .LBB0_226

.LBB0_226:
	s_cmp_eq_u32 s98, 0
	s_cbranch_scc1 .Lp01_to_barrier
	s_cmp_eq_u32 s98, 4
	s_cbranch_scc1 .Lp2slot_ret
	v_readlane_b32 s73, v254, 20
	s_cmp_eq_u32 s98, 1
	s_cbranch_scc1 .LBB0_281
	s_branch .Lp1_begin2

.Lp01_items:
	s_add_u32 s2, s82, 0x1000000
	s_addc_u32 s3, s83, 0
	s_add_u32 s14, s82, 0x1500000
	s_addc_u32 s15, s83, 0
	s_add_u32 s12, s82, 0x1600000
	s_addc_u32 s13, s83, 0
	s_mov_b32 s73, s99
	s_branch .Lp01_bb36

.LBB0_367:
	s_cmpk_lt_i32 s64, 0x80
	s_cbranch_scc1 .Lp2slot_skip
	s_waitcnt vmcnt(0) lgkmcnt(0)
	s_barrier
	v_writelane_b32 v250, s12, 0
	v_writelane_b32 v250, s13, 1
	v_writelane_b32 v250, s14, 2
	v_writelane_b32 v250, s15, 3
	v_writelane_b32 v250, s18, 4
	v_writelane_b32 v250, s19, 5
	v_writelane_b32 v250, s20, 6
	v_writelane_b32 v250, s21, 7
	v_writelane_b32 v250, s22, 8
	v_writelane_b32 v250, s23, 9
	v_writelane_b32 v250, s24, 10
	v_writelane_b32 v250, s25, 11
	v_writelane_b32 v250, s26, 12
	v_writelane_b32 v250, s27, 13
	v_writelane_b32 v250, s28, 14
	v_writelane_b32 v250, s46, 15
	v_writelane_b32 v250, s47, 16
	v_writelane_b32 v250, s49, 17
	v_writelane_b32 v250, s50, 18
	v_writelane_b32 v250, s52, 19
	v_writelane_b32 v250, s73, 20
	v_mov_b32_e32 v251, v3
	v_mbcnt_lo_u32_b32 v141, -1, 0
	v_mbcnt_hi_u32_b32 v141, -1, v141
	v_and_b32_e32 v140, 63, v141
	s_movk_i32 s52, 0x400
	s_mov_b32 s98, 4
	s_branch .Lp01_items
.Lp2slot_ret:
	s_waitcnt vmcnt(0) lgkmcnt(0)
	v_readlane_b32 s12, v250, 0
	v_readlane_b32 s13, v250, 1
	v_readlane_b32 s14, v250, 2
	v_readlane_b32 s15, v250, 3
	v_readlane_b32 s18, v250, 4
	v_readlane_b32 s19, v250, 5
	v_readlane_b32 s20, v250, 6
	v_readlane_b32 s21, v250, 7
	v_readlane_b32 s22, v250, 8
	v_readlane_b32 s23, v250, 9
	v_readlane_b32 s24, v250, 10
	v_readlane_b32 s25, v250, 11
	v_readlane_b32 s26, v250, 12
	v_readlane_b32 s27, v250, 13
	v_readlane_b32 s28, v250, 14
	v_readlane_b32 s46, v250, 15
	v_readlane_b32 s47, v250, 16
	v_readlane_b32 s49, v250, 17
	v_readlane_b32 s50, v250, 18
	v_readlane_b32 s52, v250, 19
	v_readlane_b32 s73, v250, 20
	v_mov_b32_e32 v3, v251
	s_mov_b32 s98, 3
